# RWKV step loop in packed f32 (v_pk_mul/fma) hand-scheduled; helper waves: convert wait no longer blocks on the y store (vmcnt 7 for waves 4,5)
# speedup vs baseline: 1.0016x; 1.0016x over previous
; __device__ __forceinline__ void rwkv_item(PC p, int wv, int L, int item, LAS unsigned char* lds) {
;     ...
;         if (wv < 4) {
;         f32x2 rA, rB, wA, wB, kA, kB, bA, bB, eA, eB; float vvn;
;         RW_LD(0)
; #pragma unroll
;         for (int s = 0; s < 32; ++s) {
;             const f32x2 r0 = rA, r1 = rB, w0 = wA, w1 = wB, k0 = kA, k1 = kB, b0 = bA, b1 = bB, e0 = eA, e1 = eB; const float vv = vvn;
;             if (s + 1 < 32) RW_LD(s + 1)
;             const f32x2 sa2 = SA * k0 + SB * k1;
;             const float sa = allreduce16(sa2.x + sa2.y);
;             const f32x2 sav = {sa, sa}, vvv = {vv, vv};
;             SA = SA * w0 + (vvv * e0 - sav * b0);
;             SB = SB * w1 + (vvv * e1 - sav * b1);
;             const f32x2 y2 = SA * r0 + SB * r1;
;             float yq = y2.x + y2.y;
;             yq += dppmov<0xB1>(yq); yq += dppmov<0x4E>(yq);
;             Yb[(s * 16 + rowl) * 4 + (kq >> 2)] = yq;
;         }
.Lrw_noload_L0:
.LBB0_406:
	s_and_b32 s15, s18, 1
	s_lshl_b32 s14, s15, 13
	s_add_i32 s14, s14, 0
	s_andn2_b64 vcc, exec, s[48:49]
	s_add_i32 s14, s14, 0x18000
	s_cbranch_vccnz .LBB0_408
	s_mul_i32 s19, s15, 0xc000
	s_add_i32 s19, s19, 0
	s_lshl_b32 s20, s16, 2
	v_lshl_add_u32 v26, v62, 2, s19
	s_add_i32 s19, s19, s20
	v_lshl_add_u32 v27, v61, 2, s19
	v_add3_u32 v100, s14, v63, v70
	ds_read_b128 v[0:3], v26 offset:16384
	ds_read_b128 v[4:7], v26 offset:40960
	ds_read2st64_b32 v[20:21], v27 offset0:128 offset1:129
	ds_read_b128 v[8:11], v26 offset:8192
	ds_read_b128 v[12:15], v26 offset:24576
	ds_read_b128 v[16:19], v26 offset:0
	ds_read_b128 v[28:31], v26 offset:16640
	ds_read_b128 v[32:35], v26 offset:41216
	ds_read_b128 v[36:39], v26 offset:8448
	ds_read_b128 v[72:75], v26 offset:24832
	ds_read_b128 v[76:79], v26 offset:256
	s_waitcnt lgkmcnt(5)
	v_pk_mul_f32 v[58:59], v[54:55], v[0:1]
	s_nop 0
	v_pk_fma_f32 v[58:59], v[56:57], v[2:3], v[58:59]
	s_nop 0
	v_add_f32_e32 v58, v58, v59
	s_nop 0
	v_pk_mul_f32 v[4:5], v[4:5], v[20:21] op_sel_hi:[1,0]
	v_add_f32_dpp v58, v58, v58 quad_perm:[1,0,3,2] row_mask:0xf bank_mask:0xf bound_ctrl:1
	v_pk_mul_f32 v[6:7], v[6:7], v[20:21] op_sel_hi:[1,0]
	s_nop 0
	v_add_f32_dpp v58, v58, v58 quad_perm:[2,3,0,1] row_mask:0xf bank_mask:0xf bound_ctrl:1
	v_pk_fma_f32 v[54:55], v[54:55], v[8:9], v[4:5]
	v_pk_fma_f32 v[56:57], v[56:57], v[10:11], v[6:7]
	v_add_f32_dpp v58, v58, v58 row_half_mirror row_mask:0xf bank_mask:0xf bound_ctrl:1
	s_nop 0
	ds_read_b128 v[80:83], v26 offset:16896
	v_add_f32_dpp v58, v58, v58 row_mirror row_mask:0xf bank_mask:0xf bound_ctrl:1
	v_pk_fma_f32 v[54:55], v[58:59], v[12:13], v[54:55] op_sel_hi:[0,1,1] neg_lo:[1,0,0] neg_hi:[1,0,0]
	v_pk_fma_f32 v[56:57], v[58:59], v[14:15], v[56:57] op_sel_hi:[0,1,1] neg_lo:[1,0,0] neg_hi:[1,0,0]
	ds_read_b128 v[84:87], v26 offset:41472
	ds_read2st64_b32 v[22:23], v27 offset0:130 offset1:131
	ds_read_b128 v[88:91], v26 offset:8704
	ds_read_b128 v[92:95], v26 offset:25088
	ds_read_b128 v[96:99], v26 offset:512
	s_waitcnt lgkmcnt(6)
	v_pk_mul_f32 v[58:59], v[54:55], v[28:29]
	v_pk_mul_f32 v[24:25], v[54:55], v[16:17]
	v_pk_fma_f32 v[58:59], v[56:57], v[30:31], v[58:59]
	v_pk_fma_f32 v[24:25], v[56:57], v[18:19], v[24:25]
	v_add_f32_e32 v58, v58, v59
	v_add_f32_e32 v24, v24, v25
	v_pk_mul_f32 v[32:33], v[32:33], v[20:21] op_sel:[0,1] op_sel_hi:[1,1]
	v_add_f32_dpp v58, v58, v58 quad_perm:[1,0,3,2] row_mask:0xf bank_mask:0xf bound_ctrl:1
	v_pk_mul_f32 v[34:35], v[34:35], v[20:21] op_sel:[0,1] op_sel_hi:[1,1]
	v_add_f32_dpp v24, v24, v24 quad_perm:[1,0,3,2] row_mask:0xf bank_mask:0xf bound_ctrl:1
	v_add_f32_dpp v58, v58, v58 quad_perm:[2,3,0,1] row_mask:0xf bank_mask:0xf bound_ctrl:1
	v_pk_fma_f32 v[54:55], v[54:55], v[36:37], v[32:33]
	v_pk_fma_f32 v[56:57], v[56:57], v[38:39], v[34:35]
	v_add_f32_dpp v58, v58, v58 row_half_mirror row_mask:0xf bank_mask:0xf bound_ctrl:1
	v_add_f32_dpp v24, v24, v24 quad_perm:[2,3,0,1] row_mask:0xf bank_mask:0xf bound_ctrl:1
	ds_write_b32 v100, v24 offset:0
	v_add_f32_dpp v58, v58, v58 row_mirror row_mask:0xf bank_mask:0xf bound_ctrl:1
	v_pk_fma_f32 v[54:55], v[58:59], v[72:73], v[54:55] op_sel_hi:[0,1,1] neg_lo:[1,0,0] neg_hi:[1,0,0]
	v_pk_fma_f32 v[56:57], v[58:59], v[74:75], v[56:57] op_sel_hi:[0,1,1] neg_lo:[1,0,0] neg_hi:[1,0,0]
	ds_read_b128 v[0:3], v26 offset:17152
	ds_read_b128 v[4:7], v26 offset:41728
	ds_read_b128 v[8:11], v26 offset:8960
	ds_read_b128 v[12:15], v26 offset:25344
	ds_read_b128 v[16:19], v26 offset:768
	s_waitcnt lgkmcnt(6)
	v_pk_mul_f32 v[58:59], v[54:55], v[80:81]
	v_pk_mul_f32 v[24:25], v[54:55], v[76:77]
	v_pk_fma_f32 v[58:59], v[56:57], v[82:83], v[58:59]
	v_pk_fma_f32 v[24:25], v[56:57], v[78:79], v[24:25]
	v_add_f32_e32 v58, v58, v59
	v_add_f32_e32 v24, v24, v25
	v_pk_mul_f32 v[84:85], v[84:85], v[22:23] op_sel_hi:[1,0]
	v_add_f32_dpp v58, v58, v58 quad_perm:[1,0,3,2] row_mask:0xf bank_mask:0xf bound_ctrl:1
	v_pk_mul_f32 v[86:87], v[86:87], v[22:23] op_sel_hi:[1,0]
	v_add_f32_dpp v24, v24, v24 quad_perm:[1,0,3,2] row_mask:0xf bank_mask:0xf bound_ctrl:1
	v_add_f32_dpp v58, v58, v58 quad_perm:[2,3,0,1] row_mask:0xf bank_mask:0xf bound_ctrl:1
	v_pk_fma_f32 v[54:55], v[54:55], v[88:89], v[84:85]
	v_pk_fma_f32 v[56:57], v[56:57], v[90:91], v[86:87]
	v_add_f32_dpp v58, v58, v58 row_half_mirror row_mask:0xf bank_mask:0xf bound_ctrl:1
	v_add_f32_dpp v24, v24, v24 quad_perm:[2,3,0,1] row_mask:0xf bank_mask:0xf bound_ctrl:1
	ds_write_b32 v100, v24 offset:256
	v_add_f32_dpp v58, v58, v58 row_mirror row_mask:0xf bank_mask:0xf bound_ctrl:1
	v_pk_fma_f32 v[54:55], v[58:59], v[92:93], v[54:55] op_sel_hi:[0,1,1] neg_lo:[1,0,0] neg_hi:[1,0,0]
	v_pk_fma_f32 v[56:57], v[58:59], v[94:95], v[56:57] op_sel_hi:[0,1,1] neg_lo:[1,0,0] neg_hi:[1,0,0]
	ds_read_b128 v[28:31], v26 offset:17408
	ds_read_b128 v[32:35], v26 offset:41984
	ds_read2st64_b32 v[20:21], v27 offset0:132 offset1:133
	ds_read_b128 v[36:39], v26 offset:9216
	ds_read_b128 v[72:75], v26 offset:25600
	ds_read_b128 v[76:79], v26 offset:1024
	s_waitcnt lgkmcnt(7)
; __device__ __forceinline__ void rwkv_item(PC p, int wv, int L, int item, LAS unsigned char* lds) {
;     ...
;         for (int s = 0; s < 32; ++s) {
;             const f32x2 r0 = rA, r1 = rB, w0 = wA, w1 = wB, k0 = kA, k1 = kB, b0 = bA, b1 = bB, e0 = eA, e1 = eB; const float vv = vvn;
;             if (s + 1 < 32) RW_LD(s + 1)
;             const f32x2 sa2 = SA * k0 + SB * k1;
;             const float sa = allreduce16(sa2.x + sa2.y);
;             const f32x2 sav = {sa, sa}, vvv = {vv, vv};
;             SA = SA * w0 + (vvv * e0 - sav * b0);
;             SB = SB * w1 + (vvv * e1 - sav * b1);
;             const f32x2 y2 = SA * r0 + SB * r1;
;             float yq = y2.x + y2.y;
;             yq += dppmov<0xB1>(yq); yq += dppmov<0x4E>(yq);
;             Yb[(s * 16 + rowl) * 4 + (kq >> 2)] = yq;
;         }
	v_pk_mul_f32 v[58:59], v[54:55], v[0:1]
	v_pk_mul_f32 v[24:25], v[54:55], v[96:97]
	v_pk_fma_f32 v[58:59], v[56:57], v[2:3], v[58:59]
	v_pk_fma_f32 v[24:25], v[56:57], v[98:99], v[24:25]
	v_add_f32_e32 v58, v58, v59
	v_add_f32_e32 v24, v24, v25
	v_pk_mul_f32 v[4:5], v[4:5], v[22:23] op_sel:[0,1] op_sel_hi:[1,1]
	v_add_f32_dpp v58, v58, v58 quad_perm:[1,0,3,2] row_mask:0xf bank_mask:0xf bound_ctrl:1
	v_pk_mul_f32 v[6:7], v[6:7], v[22:23] op_sel:[0,1] op_sel_hi:[1,1]
	v_add_f32_dpp v24, v24, v24 quad_perm:[1,0,3,2] row_mask:0xf bank_mask:0xf bound_ctrl:1
	v_add_f32_dpp v58, v58, v58 quad_perm:[2,3,0,1] row_mask:0xf bank_mask:0xf bound_ctrl:1
	v_pk_fma_f32 v[54:55], v[54:55], v[8:9], v[4:5]
	v_pk_fma_f32 v[56:57], v[56:57], v[10:11], v[6:7]
	v_add_f32_dpp v58, v58, v58 row_half_mirror row_mask:0xf bank_mask:0xf bound_ctrl:1
	v_add_f32_dpp v24, v24, v24 quad_perm:[2,3,0,1] row_mask:0xf bank_mask:0xf bound_ctrl:1
	ds_write_b32 v100, v24 offset:512
	v_add_f32_dpp v58, v58, v58 row_mirror row_mask:0xf bank_mask:0xf bound_ctrl:1
	v_pk_fma_f32 v[54:55], v[58:59], v[12:13], v[54:55] op_sel_hi:[0,1,1] neg_lo:[1,0,0] neg_hi:[1,0,0]
	v_pk_fma_f32 v[56:57], v[58:59], v[14:15], v[56:57] op_sel_hi:[0,1,1] neg_lo:[1,0,0] neg_hi:[1,0,0]
	ds_read_b128 v[80:83], v26 offset:17664
	ds_read_b128 v[84:87], v26 offset:42240
	ds_read_b128 v[88:91], v26 offset:9472
	ds_read_b128 v[92:95], v26 offset:25856
	ds_read_b128 v[96:99], v26 offset:1280
	s_waitcnt lgkmcnt(6)
	v_pk_mul_f32 v[58:59], v[54:55], v[28:29]
	v_pk_mul_f32 v[24:25], v[54:55], v[16:17]
	v_pk_fma_f32 v[58:59], v[56:57], v[30:31], v[58:59]
	v_pk_fma_f32 v[24:25], v[56:57], v[18:19], v[24:25]
	v_add_f32_e32 v58, v58, v59
	v_add_f32_e32 v24, v24, v25
	v_pk_mul_f32 v[32:33], v[32:33], v[20:21] op_sel_hi:[1,0]
	v_add_f32_dpp v58, v58, v58 quad_perm:[1,0,3,2] row_mask:0xf bank_mask:0xf bound_ctrl:1
	v_pk_mul_f32 v[34:35], v[34:35], v[20:21] op_sel_hi:[1,0]
	v_add_f32_dpp v24, v24, v24 quad_perm:[1,0,3,2] row_mask:0xf bank_mask:0xf bound_ctrl:1
	v_add_f32_dpp v58, v58, v58 quad_perm:[2,3,0,1] row_mask:0xf bank_mask:0xf bound_ctrl:1
	v_pk_fma_f32 v[54:55], v[54:55], v[36:37], v[32:33]
	v_pk_fma_f32 v[56:57], v[56:57], v[38:39], v[34:35]
	v_add_f32_dpp v58, v58, v58 row_half_mirror row_mask:0xf bank_mask:0xf bound_ctrl:1
	v_add_f32_dpp v24, v24, v24 quad_perm:[2,3,0,1] row_mask:0xf bank_mask:0xf bound_ctrl:1
	ds_write_b32 v100, v24 offset:768
	v_add_f32_dpp v58, v58, v58 row_mirror row_mask:0xf bank_mask:0xf bound_ctrl:1
	v_pk_fma_f32 v[54:55], v[58:59], v[72:73], v[54:55] op_sel_hi:[0,1,1] neg_lo:[1,0,0] neg_hi:[1,0,0]
	v_pk_fma_f32 v[56:57], v[58:59], v[74:75], v[56:57] op_sel_hi:[0,1,1] neg_lo:[1,0,0] neg_hi:[1,0,0]
	ds_read_b128 v[0:3], v26 offset:17920
	ds_read_b128 v[4:7], v26 offset:42496
	ds_read2st64_b32 v[22:23], v27 offset0:134 offset1:135
	ds_read_b128 v[8:11], v26 offset:9728
	ds_read_b128 v[12:15], v26 offset:26112
	ds_read_b128 v[16:19], v26 offset:1536
	s_waitcnt lgkmcnt(7)
	v_pk_mul_f32 v[58:59], v[54:55], v[80:81]
	v_pk_mul_f32 v[24:25], v[54:55], v[76:77]
	v_pk_fma_f32 v[58:59], v[56:57], v[82:83], v[58:59]
	v_pk_fma_f32 v[24:25], v[56:57], v[78:79], v[24:25]
	v_add_f32_e32 v58, v58, v59
	v_add_f32_e32 v24, v24, v25
	v_pk_mul_f32 v[84:85], v[84:85], v[20:21] op_sel:[0,1] op_sel_hi:[1,1]
	v_add_f32_dpp v58, v58, v58 quad_perm:[1,0,3,2] row_mask:0xf bank_mask:0xf bound_ctrl:1
	v_pk_mul_f32 v[86:87], v[86:87], v[20:21] op_sel:[0,1] op_sel_hi:[1,1]
	v_add_f32_dpp v24, v24, v24 quad_perm:[1,0,3,2] row_mask:0xf bank_mask:0xf bound_ctrl:1
	v_add_f32_dpp v58, v58, v58 quad_perm:[2,3,0,1] row_mask:0xf bank_mask:0xf bound_ctrl:1
	v_pk_fma_f32 v[54:55], v[54:55], v[88:89], v[84:85]
	v_pk_fma_f32 v[56:57], v[56:57], v[90:91], v[86:87]
	v_add_f32_dpp v58, v58, v58 row_half_mirror row_mask:0xf bank_mask:0xf bound_ctrl:1
	v_add_f32_dpp v24, v24, v24 quad_perm:[2,3,0,1] row_mask:0xf bank_mask:0xf bound_ctrl:1
	ds_write_b32 v100, v24 offset:1024
	v_add_f32_dpp v58, v58, v58 row_mirror row_mask:0xf bank_mask:0xf bound_ctrl:1
	v_pk_fma_f32 v[54:55], v[58:59], v[92:93], v[54:55] op_sel_hi:[0,1,1] neg_lo:[1,0,0] neg_hi:[1,0,0]
	v_pk_fma_f32 v[56:57], v[58:59], v[94:95], v[56:57] op_sel_hi:[0,1,1] neg_lo:[1,0,0] neg_hi:[1,0,0]
	ds_read_b128 v[28:31], v26 offset:18176
	ds_read_b128 v[32:35], v26 offset:42752
	ds_read_b128 v[36:39], v26 offset:9984
	ds_read_b128 v[72:75], v26 offset:26368
	ds_read_b128 v[76:79], v26 offset:1792
	s_waitcnt lgkmcnt(6)
	v_pk_mul_f32 v[58:59], v[54:55], v[0:1]
	v_pk_mul_f32 v[24:25], v[54:55], v[96:97]
	v_pk_fma_f32 v[58:59], v[56:57], v[2:3], v[58:59]
	v_pk_fma_f32 v[24:25], v[56:57], v[98:99], v[24:25]
	v_add_f32_e32 v58, v58, v59
	v_add_f32_e32 v24, v24, v25
	v_pk_mul_f32 v[4:5], v[4:5], v[22:23] op_sel_hi:[1,0]
	v_add_f32_dpp v58, v58, v58 quad_perm:[1,0,3,2] row_mask:0xf bank_mask:0xf bound_ctrl:1
	v_pk_mul_f32 v[6:7], v[6:7], v[22:23] op_sel_hi:[1,0]
	v_add_f32_dpp v24, v24, v24 quad_perm:[1,0,3,2] row_mask:0xf bank_mask:0xf bound_ctrl:1
	v_add_f32_dpp v58, v58, v58 quad_perm:[2,3,0,1] row_mask:0xf bank_mask:0xf bound_ctrl:1
	v_pk_fma_f32 v[54:55], v[54:55], v[8:9], v[4:5]
	v_pk_fma_f32 v[56:57], v[56:57], v[10:11], v[6:7]
	v_add_f32_dpp v58, v58, v58 row_half_mirror row_mask:0xf bank_mask:0xf bound_ctrl:1
	v_add_f32_dpp v24, v24, v24 quad_perm:[2,3,0,1] row_mask:0xf bank_mask:0xf bound_ctrl:1
	ds_write_b32 v100, v24 offset:1280
	v_add_f32_dpp v58, v58, v58 row_mirror row_mask:0xf bank_mask:0xf bound_ctrl:1
	v_pk_fma_f32 v[54:55], v[58:59], v[12:13], v[54:55] op_sel_hi:[0,1,1] neg_lo:[1,0,0] neg_hi:[1,0,0]
	v_pk_fma_f32 v[56:57], v[58:59], v[14:15], v[56:57] op_sel_hi:[0,1,1] neg_lo:[1,0,0] neg_hi:[1,0,0]
	ds_read_b128 v[80:83], v26 offset:18432
	ds_read_b128 v[84:87], v26 offset:43008
	ds_read2st64_b32 v[20:21], v27 offset0:136 offset1:137
	ds_read_b128 v[88:91], v26 offset:10240
	ds_read_b128 v[92:95], v26 offset:26624
	ds_read_b128 v[96:99], v26 offset:2048
	s_waitcnt lgkmcnt(7)
; __device__ __forceinline__ void rwkv_item(PC p, int wv, int L, int item, LAS unsigned char* lds) {
;     ...
;         for (int s = 0; s < 32; ++s) {
;             const f32x2 r0 = rA, r1 = rB, w0 = wA, w1 = wB, k0 = kA, k1 = kB, b0 = bA, b1 = bB, e0 = eA, e1 = eB; const float vv = vvn;
;             if (s + 1 < 32) RW_LD(s + 1)
;             const f32x2 sa2 = SA * k0 + SB * k1;
;             const float sa = allreduce16(sa2.x + sa2.y);
;             const f32x2 sav = {sa, sa}, vvv = {vv, vv};
;             SA = SA * w0 + (vvv * e0 - sav * b0);
;             SB = SB * w1 + (vvv * e1 - sav * b1);
;             const f32x2 y2 = SA * r0 + SB * r1;
;             float yq = y2.x + y2.y;
;             yq += dppmov<0xB1>(yq); yq += dppmov<0x4E>(yq);
;             Yb[(s * 16 + rowl) * 4 + (kq >> 2)] = yq;
;         }
	v_pk_mul_f32 v[58:59], v[54:55], v[28:29]
	v_pk_mul_f32 v[24:25], v[54:55], v[16:17]
	v_pk_fma_f32 v[58:59], v[56:57], v[30:31], v[58:59]
	v_pk_fma_f32 v[24:25], v[56:57], v[18:19], v[24:25]
	v_add_f32_e32 v58, v58, v59
	v_add_f32_e32 v24, v24, v25
	v_pk_mul_f32 v[32:33], v[32:33], v[22:23] op_sel:[0,1] op_sel_hi:[1,1]
	v_add_f32_dpp v58, v58, v58 quad_perm:[1,0,3,2] row_mask:0xf bank_mask:0xf bound_ctrl:1
	v_pk_mul_f32 v[34:35], v[34:35], v[22:23] op_sel:[0,1] op_sel_hi:[1,1]
	v_add_f32_dpp v24, v24, v24 quad_perm:[1,0,3,2] row_mask:0xf bank_mask:0xf bound_ctrl:1
	v_add_f32_dpp v58, v58, v58 quad_perm:[2,3,0,1] row_mask:0xf bank_mask:0xf bound_ctrl:1
	v_pk_fma_f32 v[54:55], v[54:55], v[36:37], v[32:33]
	v_pk_fma_f32 v[56:57], v[56:57], v[38:39], v[34:35]
	v_add_f32_dpp v58, v58, v58 row_half_mirror row_mask:0xf bank_mask:0xf bound_ctrl:1
	v_add_f32_dpp v24, v24, v24 quad_perm:[2,3,0,1] row_mask:0xf bank_mask:0xf bound_ctrl:1
	ds_write_b32 v100, v24 offset:1536
	v_add_f32_dpp v58, v58, v58 row_mirror row_mask:0xf bank_mask:0xf bound_ctrl:1
	v_pk_fma_f32 v[54:55], v[58:59], v[72:73], v[54:55] op_sel_hi:[0,1,1] neg_lo:[1,0,0] neg_hi:[1,0,0]
	v_pk_fma_f32 v[56:57], v[58:59], v[74:75], v[56:57] op_sel_hi:[0,1,1] neg_lo:[1,0,0] neg_hi:[1,0,0]
	ds_read_b128 v[0:3], v26 offset:18688
	ds_read_b128 v[4:7], v26 offset:43264
	ds_read_b128 v[8:11], v26 offset:10496
	ds_read_b128 v[12:15], v26 offset:26880
	ds_read_b128 v[16:19], v26 offset:2304
	s_waitcnt lgkmcnt(6)
	v_pk_mul_f32 v[58:59], v[54:55], v[80:81]
	v_pk_mul_f32 v[24:25], v[54:55], v[76:77]
	v_pk_fma_f32 v[58:59], v[56:57], v[82:83], v[58:59]
	v_pk_fma_f32 v[24:25], v[56:57], v[78:79], v[24:25]
	v_add_f32_e32 v58, v58, v59
	v_add_f32_e32 v24, v24, v25
	v_pk_mul_f32 v[84:85], v[84:85], v[20:21] op_sel_hi:[1,0]
	v_add_f32_dpp v58, v58, v58 quad_perm:[1,0,3,2] row_mask:0xf bank_mask:0xf bound_ctrl:1
	v_pk_mul_f32 v[86:87], v[86:87], v[20:21] op_sel_hi:[1,0]
	v_add_f32_dpp v24, v24, v24 quad_perm:[1,0,3,2] row_mask:0xf bank_mask:0xf bound_ctrl:1
	v_add_f32_dpp v58, v58, v58 quad_perm:[2,3,0,1] row_mask:0xf bank_mask:0xf bound_ctrl:1
	v_pk_fma_f32 v[54:55], v[54:55], v[88:89], v[84:85]
	v_pk_fma_f32 v[56:57], v[56:57], v[90:91], v[86:87]
	v_add_f32_dpp v58, v58, v58 row_half_mirror row_mask:0xf bank_mask:0xf bound_ctrl:1
	v_add_f32_dpp v24, v24, v24 quad_perm:[2,3,0,1] row_mask:0xf bank_mask:0xf bound_ctrl:1
	ds_write_b32 v100, v24 offset:1792
	v_add_f32_dpp v58, v58, v58 row_mirror row_mask:0xf bank_mask:0xf bound_ctrl:1
	v_pk_fma_f32 v[54:55], v[58:59], v[92:93], v[54:55] op_sel_hi:[0,1,1] neg_lo:[1,0,0] neg_hi:[1,0,0]
	v_pk_fma_f32 v[56:57], v[58:59], v[94:95], v[56:57] op_sel_hi:[0,1,1] neg_lo:[1,0,0] neg_hi:[1,0,0]
	ds_read_b128 v[28:31], v26 offset:18944
	ds_read_b128 v[32:35], v26 offset:43520
	ds_read2st64_b32 v[22:23], v27 offset0:138 offset1:139
	ds_read_b128 v[36:39], v26 offset:10752
	ds_read_b128 v[72:75], v26 offset:27136
	ds_read_b128 v[76:79], v26 offset:2560
	s_waitcnt lgkmcnt(7)
	v_pk_mul_f32 v[58:59], v[54:55], v[0:1]
	v_pk_mul_f32 v[24:25], v[54:55], v[96:97]
	v_pk_fma_f32 v[58:59], v[56:57], v[2:3], v[58:59]
	v_pk_fma_f32 v[24:25], v[56:57], v[98:99], v[24:25]
	v_add_f32_e32 v58, v58, v59
	v_add_f32_e32 v24, v24, v25
	v_pk_mul_f32 v[4:5], v[4:5], v[20:21] op_sel:[0,1] op_sel_hi:[1,1]
	v_add_f32_dpp v58, v58, v58 quad_perm:[1,0,3,2] row_mask:0xf bank_mask:0xf bound_ctrl:1
	v_pk_mul_f32 v[6:7], v[6:7], v[20:21] op_sel:[0,1] op_sel_hi:[1,1]
	v_add_f32_dpp v24, v24, v24 quad_perm:[1,0,3,2] row_mask:0xf bank_mask:0xf bound_ctrl:1
	v_add_f32_dpp v58, v58, v58 quad_perm:[2,3,0,1] row_mask:0xf bank_mask:0xf bound_ctrl:1
	v_pk_fma_f32 v[54:55], v[54:55], v[8:9], v[4:5]
	v_pk_fma_f32 v[56:57], v[56:57], v[10:11], v[6:7]
	v_add_f32_dpp v58, v58, v58 row_half_mirror row_mask:0xf bank_mask:0xf bound_ctrl:1
	v_add_f32_dpp v24, v24, v24 quad_perm:[2,3,0,1] row_mask:0xf bank_mask:0xf bound_ctrl:1
	ds_write_b32 v100, v24 offset:2048
	v_add_f32_dpp v58, v58, v58 row_mirror row_mask:0xf bank_mask:0xf bound_ctrl:1
	v_pk_fma_f32 v[54:55], v[58:59], v[12:13], v[54:55] op_sel_hi:[0,1,1] neg_lo:[1,0,0] neg_hi:[1,0,0]
	v_pk_fma_f32 v[56:57], v[58:59], v[14:15], v[56:57] op_sel_hi:[0,1,1] neg_lo:[1,0,0] neg_hi:[1,0,0]
	ds_read_b128 v[80:83], v26 offset:19200
	ds_read_b128 v[84:87], v26 offset:43776
	ds_read_b128 v[88:91], v26 offset:11008
	ds_read_b128 v[92:95], v26 offset:27392
	ds_read_b128 v[96:99], v26 offset:2816
	s_waitcnt lgkmcnt(6)
	v_pk_mul_f32 v[58:59], v[54:55], v[28:29]
	v_pk_mul_f32 v[24:25], v[54:55], v[16:17]
	v_pk_fma_f32 v[58:59], v[56:57], v[30:31], v[58:59]
	v_pk_fma_f32 v[24:25], v[56:57], v[18:19], v[24:25]
	v_add_f32_e32 v58, v58, v59
	v_add_f32_e32 v24, v24, v25
	v_pk_mul_f32 v[32:33], v[32:33], v[22:23] op_sel_hi:[1,0]
	v_add_f32_dpp v58, v58, v58 quad_perm:[1,0,3,2] row_mask:0xf bank_mask:0xf bound_ctrl:1
	v_pk_mul_f32 v[34:35], v[34:35], v[22:23] op_sel_hi:[1,0]
	v_add_f32_dpp v24, v24, v24 quad_perm:[1,0,3,2] row_mask:0xf bank_mask:0xf bound_ctrl:1
	v_add_f32_dpp v58, v58, v58 quad_perm:[2,3,0,1] row_mask:0xf bank_mask:0xf bound_ctrl:1
	v_pk_fma_f32 v[54:55], v[54:55], v[36:37], v[32:33]
	v_pk_fma_f32 v[56:57], v[56:57], v[38:39], v[34:35]
	v_add_f32_dpp v58, v58, v58 row_half_mirror row_mask:0xf bank_mask:0xf bound_ctrl:1
	v_add_f32_dpp v24, v24, v24 quad_perm:[2,3,0,1] row_mask:0xf bank_mask:0xf bound_ctrl:1
	ds_write_b32 v100, v24 offset:2304
	v_add_f32_dpp v58, v58, v58 row_mirror row_mask:0xf bank_mask:0xf bound_ctrl:1
	v_pk_fma_f32 v[54:55], v[58:59], v[72:73], v[54:55] op_sel_hi:[0,1,1] neg_lo:[1,0,0] neg_hi:[1,0,0]
	v_pk_fma_f32 v[56:57], v[58:59], v[74:75], v[56:57] op_sel_hi:[0,1,1] neg_lo:[1,0,0] neg_hi:[1,0,0]
	ds_read_b128 v[0:3], v26 offset:19456
	ds_read_b128 v[4:7], v26 offset:44032
	ds_read2st64_b32 v[20:21], v27 offset0:140 offset1:141
	ds_read_b128 v[8:11], v26 offset:11264
	ds_read_b128 v[12:15], v26 offset:27648
	ds_read_b128 v[16:19], v26 offset:3072
	s_waitcnt lgkmcnt(7)
; __device__ __forceinline__ void rwkv_item(PC p, int wv, int L, int item, LAS unsigned char* lds) {
;     ...
;         for (int s = 0; s < 32; ++s) {
;             const f32x2 r0 = rA, r1 = rB, w0 = wA, w1 = wB, k0 = kA, k1 = kB, b0 = bA, b1 = bB, e0 = eA, e1 = eB; const float vv = vvn;
;             if (s + 1 < 32) RW_LD(s + 1)
;             const f32x2 sa2 = SA * k0 + SB * k1;
;             const float sa = allreduce16(sa2.x + sa2.y);
;             const f32x2 sav = {sa, sa}, vvv = {vv, vv};
;             SA = SA * w0 + (vvv * e0 - sav * b0);
;             SB = SB * w1 + (vvv * e1 - sav * b1);
;             const f32x2 y2 = SA * r0 + SB * r1;
;             float yq = y2.x + y2.y;
;             yq += dppmov<0xB1>(yq); yq += dppmov<0x4E>(yq);
;             Yb[(s * 16 + rowl) * 4 + (kq >> 2)] = yq;
;         }
	v_pk_mul_f32 v[58:59], v[54:55], v[80:81]
	v_pk_mul_f32 v[24:25], v[54:55], v[76:77]
	v_pk_fma_f32 v[58:59], v[56:57], v[82:83], v[58:59]
	v_pk_fma_f32 v[24:25], v[56:57], v[78:79], v[24:25]
	v_add_f32_e32 v58, v58, v59
	v_add_f32_e32 v24, v24, v25
	v_pk_mul_f32 v[84:85], v[84:85], v[22:23] op_sel:[0,1] op_sel_hi:[1,1]
	v_add_f32_dpp v58, v58, v58 quad_perm:[1,0,3,2] row_mask:0xf bank_mask:0xf bound_ctrl:1
	v_pk_mul_f32 v[86:87], v[86:87], v[22:23] op_sel:[0,1] op_sel_hi:[1,1]
	v_add_f32_dpp v24, v24, v24 quad_perm:[1,0,3,2] row_mask:0xf bank_mask:0xf bound_ctrl:1
	v_add_f32_dpp v58, v58, v58 quad_perm:[2,3,0,1] row_mask:0xf bank_mask:0xf bound_ctrl:1
	v_pk_fma_f32 v[54:55], v[54:55], v[88:89], v[84:85]
	v_pk_fma_f32 v[56:57], v[56:57], v[90:91], v[86:87]
	v_add_f32_dpp v58, v58, v58 row_half_mirror row_mask:0xf bank_mask:0xf bound_ctrl:1
	v_add_f32_dpp v24, v24, v24 quad_perm:[2,3,0,1] row_mask:0xf bank_mask:0xf bound_ctrl:1
	ds_write_b32 v100, v24 offset:2560
	v_add_f32_dpp v58, v58, v58 row_mirror row_mask:0xf bank_mask:0xf bound_ctrl:1
	v_pk_fma_f32 v[54:55], v[58:59], v[92:93], v[54:55] op_sel_hi:[0,1,1] neg_lo:[1,0,0] neg_hi:[1,0,0]
	v_pk_fma_f32 v[56:57], v[58:59], v[94:95], v[56:57] op_sel_hi:[0,1,1] neg_lo:[1,0,0] neg_hi:[1,0,0]
	ds_read_b128 v[28:31], v26 offset:19712
	ds_read_b128 v[32:35], v26 offset:44288
	ds_read_b128 v[36:39], v26 offset:11520
	ds_read_b128 v[72:75], v26 offset:27904
	ds_read_b128 v[76:79], v26 offset:3328
	s_waitcnt lgkmcnt(6)
	v_pk_mul_f32 v[58:59], v[54:55], v[0:1]
	v_pk_mul_f32 v[24:25], v[54:55], v[96:97]
	v_pk_fma_f32 v[58:59], v[56:57], v[2:3], v[58:59]
	v_pk_fma_f32 v[24:25], v[56:57], v[98:99], v[24:25]
	v_add_f32_e32 v58, v58, v59
	v_add_f32_e32 v24, v24, v25
	v_pk_mul_f32 v[4:5], v[4:5], v[20:21] op_sel_hi:[1,0]
	v_add_f32_dpp v58, v58, v58 quad_perm:[1,0,3,2] row_mask:0xf bank_mask:0xf bound_ctrl:1
	v_pk_mul_f32 v[6:7], v[6:7], v[20:21] op_sel_hi:[1,0]
	v_add_f32_dpp v24, v24, v24 quad_perm:[1,0,3,2] row_mask:0xf bank_mask:0xf bound_ctrl:1
	v_add_f32_dpp v58, v58, v58 quad_perm:[2,3,0,1] row_mask:0xf bank_mask:0xf bound_ctrl:1
	v_pk_fma_f32 v[54:55], v[54:55], v[8:9], v[4:5]
	v_pk_fma_f32 v[56:57], v[56:57], v[10:11], v[6:7]
	v_add_f32_dpp v58, v58, v58 row_half_mirror row_mask:0xf bank_mask:0xf bound_ctrl:1
	v_add_f32_dpp v24, v24, v24 quad_perm:[2,3,0,1] row_mask:0xf bank_mask:0xf bound_ctrl:1
	ds_write_b32 v100, v24 offset:2816
	v_add_f32_dpp v58, v58, v58 row_mirror row_mask:0xf bank_mask:0xf bound_ctrl:1
	v_pk_fma_f32 v[54:55], v[58:59], v[12:13], v[54:55] op_sel_hi:[0,1,1] neg_lo:[1,0,0] neg_hi:[1,0,0]
	v_pk_fma_f32 v[56:57], v[58:59], v[14:15], v[56:57] op_sel_hi:[0,1,1] neg_lo:[1,0,0] neg_hi:[1,0,0]
	ds_read_b128 v[80:83], v26 offset:19968
	ds_read_b128 v[84:87], v26 offset:44544
	ds_read2st64_b32 v[22:23], v27 offset0:142 offset1:143
	ds_read_b128 v[88:91], v26 offset:11776
	ds_read_b128 v[92:95], v26 offset:28160
	ds_read_b128 v[96:99], v26 offset:3584
	s_waitcnt lgkmcnt(7)
	v_pk_mul_f32 v[58:59], v[54:55], v[28:29]
	v_pk_mul_f32 v[24:25], v[54:55], v[16:17]
	v_pk_fma_f32 v[58:59], v[56:57], v[30:31], v[58:59]
	v_pk_fma_f32 v[24:25], v[56:57], v[18:19], v[24:25]
	v_add_f32_e32 v58, v58, v59
	v_add_f32_e32 v24, v24, v25
	v_pk_mul_f32 v[32:33], v[32:33], v[20:21] op_sel:[0,1] op_sel_hi:[1,1]
	v_add_f32_dpp v58, v58, v58 quad_perm:[1,0,3,2] row_mask:0xf bank_mask:0xf bound_ctrl:1
	v_pk_mul_f32 v[34:35], v[34:35], v[20:21] op_sel:[0,1] op_sel_hi:[1,1]
	v_add_f32_dpp v24, v24, v24 quad_perm:[1,0,3,2] row_mask:0xf bank_mask:0xf bound_ctrl:1
	v_add_f32_dpp v58, v58, v58 quad_perm:[2,3,0,1] row_mask:0xf bank_mask:0xf bound_ctrl:1
	v_pk_fma_f32 v[54:55], v[54:55], v[36:37], v[32:33]
	v_pk_fma_f32 v[56:57], v[56:57], v[38:39], v[34:35]
	v_add_f32_dpp v58, v58, v58 row_half_mirror row_mask:0xf bank_mask:0xf bound_ctrl:1
	v_add_f32_dpp v24, v24, v24 quad_perm:[2,3,0,1] row_mask:0xf bank_mask:0xf bound_ctrl:1
	ds_write_b32 v100, v24 offset:3072
	v_add_f32_dpp v58, v58, v58 row_mirror row_mask:0xf bank_mask:0xf bound_ctrl:1
	v_pk_fma_f32 v[54:55], v[58:59], v[72:73], v[54:55] op_sel_hi:[0,1,1] neg_lo:[1,0,0] neg_hi:[1,0,0]
	v_pk_fma_f32 v[56:57], v[58:59], v[74:75], v[56:57] op_sel_hi:[0,1,1] neg_lo:[1,0,0] neg_hi:[1,0,0]
	ds_read_b128 v[0:3], v26 offset:20224
	ds_read_b128 v[4:7], v26 offset:44800
	ds_read_b128 v[8:11], v26 offset:12032
	ds_read_b128 v[12:15], v26 offset:28416
	ds_read_b128 v[16:19], v26 offset:3840
	s_waitcnt lgkmcnt(6)
	v_pk_mul_f32 v[58:59], v[54:55], v[80:81]
	v_pk_mul_f32 v[24:25], v[54:55], v[76:77]
	v_pk_fma_f32 v[58:59], v[56:57], v[82:83], v[58:59]
	v_pk_fma_f32 v[24:25], v[56:57], v[78:79], v[24:25]
	v_add_f32_e32 v58, v58, v59
	v_add_f32_e32 v24, v24, v25
	v_pk_mul_f32 v[84:85], v[84:85], v[22:23] op_sel_hi:[1,0]
	v_add_f32_dpp v58, v58, v58 quad_perm:[1,0,3,2] row_mask:0xf bank_mask:0xf bound_ctrl:1
	v_pk_mul_f32 v[86:87], v[86:87], v[22:23] op_sel_hi:[1,0]
	v_add_f32_dpp v24, v24, v24 quad_perm:[1,0,3,2] row_mask:0xf bank_mask:0xf bound_ctrl:1
	v_add_f32_dpp v58, v58, v58 quad_perm:[2,3,0,1] row_mask:0xf bank_mask:0xf bound_ctrl:1
	v_pk_fma_f32 v[54:55], v[54:55], v[88:89], v[84:85]
	v_pk_fma_f32 v[56:57], v[56:57], v[90:91], v[86:87]
	v_add_f32_dpp v58, v58, v58 row_half_mirror row_mask:0xf bank_mask:0xf bound_ctrl:1
	v_add_f32_dpp v24, v24, v24 quad_perm:[2,3,0,1] row_mask:0xf bank_mask:0xf bound_ctrl:1
	ds_write_b32 v100, v24 offset:3328
	v_add_f32_dpp v58, v58, v58 row_mirror row_mask:0xf bank_mask:0xf bound_ctrl:1
	v_pk_fma_f32 v[54:55], v[58:59], v[92:93], v[54:55] op_sel_hi:[0,1,1] neg_lo:[1,0,0] neg_hi:[1,0,0]
	v_pk_fma_f32 v[56:57], v[58:59], v[94:95], v[56:57] op_sel_hi:[0,1,1] neg_lo:[1,0,0] neg_hi:[1,0,0]
	ds_read_b128 v[28:31], v26 offset:20480
	ds_read_b128 v[32:35], v26 offset:45056
	ds_read2st64_b32 v[20:21], v27 offset0:144 offset1:145
	ds_read_b128 v[36:39], v26 offset:12288
	ds_read_b128 v[72:75], v26 offset:28672
	ds_read_b128 v[76:79], v26 offset:4096
	s_waitcnt lgkmcnt(7)
; __device__ __forceinline__ void rwkv_item(PC p, int wv, int L, int item, LAS unsigned char* lds) {
;     ...
;         if (wv < 4) {
;         f32x2 rA, rB, wA, wB, kA, kB, bA, bB, eA, eB; float vvn;
;         RW_LD(0)
; #pragma unroll
;         for (int s = 0; s < 32; ++s) {
;             const f32x2 r0 = rA, r1 = rB, w0 = wA, w1 = wB, k0 = kA, k1 = kB, b0 = bA, b1 = bB, e0 = eA, e1 = eB; const float vv = vvn;
;             if (s + 1 < 32) RW_LD(s + 1)
;             const f32x2 sa2 = SA * k0 + SB * k1;
;             const float sa = allreduce16(sa2.x + sa2.y);
;             const f32x2 sav = {sa, sa}, vvv = {vv, vv};
;             SA = SA * w0 + (vvv * e0 - sav * b0);
;             SB = SB * w1 + (vvv * e1 - sav * b1);
;             const f32x2 y2 = SA * r0 + SB * r1;
;             float yq = y2.x + y2.y;
;             yq += dppmov<0xB1>(yq); yq += dppmov<0x4E>(yq);
;             Yb[(s * 16 + rowl) * 4 + (kq >> 2)] = yq;
;         }
	v_pk_mul_f32 v[58:59], v[54:55], v[0:1]
	v_pk_mul_f32 v[24:25], v[54:55], v[96:97]
	v_pk_fma_f32 v[58:59], v[56:57], v[2:3], v[58:59]
	v_pk_fma_f32 v[24:25], v[56:57], v[98:99], v[24:25]
	v_add_f32_e32 v58, v58, v59
	v_add_f32_e32 v24, v24, v25
	v_pk_mul_f32 v[4:5], v[4:5], v[22:23] op_sel:[0,1] op_sel_hi:[1,1]
	v_add_f32_dpp v58, v58, v58 quad_perm:[1,0,3,2] row_mask:0xf bank_mask:0xf bound_ctrl:1
	v_pk_mul_f32 v[6:7], v[6:7], v[22:23] op_sel:[0,1] op_sel_hi:[1,1]
	v_add_f32_dpp v24, v24, v24 quad_perm:[1,0,3,2] row_mask:0xf bank_mask:0xf bound_ctrl:1
	v_add_f32_dpp v58, v58, v58 quad_perm:[2,3,0,1] row_mask:0xf bank_mask:0xf bound_ctrl:1
	v_pk_fma_f32 v[54:55], v[54:55], v[8:9], v[4:5]
	v_pk_fma_f32 v[56:57], v[56:57], v[10:11], v[6:7]
	v_add_f32_dpp v58, v58, v58 row_half_mirror row_mask:0xf bank_mask:0xf bound_ctrl:1
	v_add_f32_dpp v24, v24, v24 quad_perm:[2,3,0,1] row_mask:0xf bank_mask:0xf bound_ctrl:1
	ds_write_b32 v100, v24 offset:3584
	v_add_f32_dpp v58, v58, v58 row_mirror row_mask:0xf bank_mask:0xf bound_ctrl:1
	v_pk_fma_f32 v[54:55], v[58:59], v[12:13], v[54:55] op_sel_hi:[0,1,1] neg_lo:[1,0,0] neg_hi:[1,0,0]
	v_pk_fma_f32 v[56:57], v[58:59], v[14:15], v[56:57] op_sel_hi:[0,1,1] neg_lo:[1,0,0] neg_hi:[1,0,0]
	ds_read_b128 v[80:83], v26 offset:20736
	ds_read_b128 v[84:87], v26 offset:45312
	ds_read_b128 v[88:91], v26 offset:12544
	ds_read_b128 v[92:95], v26 offset:28928
	ds_read_b128 v[96:99], v26 offset:4352
	s_waitcnt lgkmcnt(6)
	v_pk_mul_f32 v[58:59], v[54:55], v[28:29]
	v_pk_mul_f32 v[24:25], v[54:55], v[16:17]
	v_pk_fma_f32 v[58:59], v[56:57], v[30:31], v[58:59]
	v_pk_fma_f32 v[24:25], v[56:57], v[18:19], v[24:25]
	v_add_f32_e32 v58, v58, v59
	v_add_f32_e32 v24, v24, v25
	v_pk_mul_f32 v[32:33], v[32:33], v[20:21] op_sel_hi:[1,0]
	v_add_f32_dpp v58, v58, v58 quad_perm:[1,0,3,2] row_mask:0xf bank_mask:0xf bound_ctrl:1
	v_pk_mul_f32 v[34:35], v[34:35], v[20:21] op_sel_hi:[1,0]
	v_add_f32_dpp v24, v24, v24 quad_perm:[1,0,3,2] row_mask:0xf bank_mask:0xf bound_ctrl:1
	v_add_f32_dpp v58, v58, v58 quad_perm:[2,3,0,1] row_mask:0xf bank_mask:0xf bound_ctrl:1
	v_pk_fma_f32 v[54:55], v[54:55], v[36:37], v[32:33]
	v_pk_fma_f32 v[56:57], v[56:57], v[38:39], v[34:35]
	v_add_f32_dpp v58, v58, v58 row_half_mirror row_mask:0xf bank_mask:0xf bound_ctrl:1
	v_add_f32_dpp v24, v24, v24 quad_perm:[2,3,0,1] row_mask:0xf bank_mask:0xf bound_ctrl:1
	ds_write_b32 v100, v24 offset:3840
	v_add_f32_dpp v58, v58, v58 row_mirror row_mask:0xf bank_mask:0xf bound_ctrl:1
	v_pk_fma_f32 v[54:55], v[58:59], v[72:73], v[54:55] op_sel_hi:[0,1,1] neg_lo:[1,0,0] neg_hi:[1,0,0]
	v_pk_fma_f32 v[56:57], v[58:59], v[74:75], v[56:57] op_sel_hi:[0,1,1] neg_lo:[1,0,0] neg_hi:[1,0,0]
	ds_read_b128 v[0:3], v26 offset:20992
	ds_read_b128 v[4:7], v26 offset:45568
	ds_read2st64_b32 v[22:23], v27 offset0:146 offset1:147
	ds_read_b128 v[8:11], v26 offset:12800
	ds_read_b128 v[12:15], v26 offset:29184
	ds_read_b128 v[16:19], v26 offset:4608
	s_waitcnt lgkmcnt(7)
	v_pk_mul_f32 v[58:59], v[54:55], v[80:81]
	v_pk_mul_f32 v[24:25], v[54:55], v[76:77]
	v_pk_fma_f32 v[58:59], v[56:57], v[82:83], v[58:59]
	v_pk_fma_f32 v[24:25], v[56:57], v[78:79], v[24:25]
	v_add_f32_e32 v58, v58, v59
	v_add_f32_e32 v24, v24, v25
	v_pk_mul_f32 v[84:85], v[84:85], v[20:21] op_sel:[0,1] op_sel_hi:[1,1]
	v_add_f32_dpp v58, v58, v58 quad_perm:[1,0,3,2] row_mask:0xf bank_mask:0xf bound_ctrl:1
	v_pk_mul_f32 v[86:87], v[86:87], v[20:21] op_sel:[0,1] op_sel_hi:[1,1]
	v_add_f32_dpp v24, v24, v24 quad_perm:[1,0,3,2] row_mask:0xf bank_mask:0xf bound_ctrl:1
	v_add_f32_dpp v58, v58, v58 quad_perm:[2,3,0,1] row_mask:0xf bank_mask:0xf bound_ctrl:1
	v_pk_fma_f32 v[54:55], v[54:55], v[88:89], v[84:85]
	v_pk_fma_f32 v[56:57], v[56:57], v[90:91], v[86:87]
	v_add_f32_dpp v58, v58, v58 row_half_mirror row_mask:0xf bank_mask:0xf bound_ctrl:1
	v_add_f32_dpp v24, v24, v24 quad_perm:[2,3,0,1] row_mask:0xf bank_mask:0xf bound_ctrl:1
	ds_write_b32 v100, v24 offset:4096
	v_add_f32_dpp v58, v58, v58 row_mirror row_mask:0xf bank_mask:0xf bound_ctrl:1
	v_pk_fma_f32 v[54:55], v[58:59], v[92:93], v[54:55] op_sel_hi:[0,1,1] neg_lo:[1,0,0] neg_hi:[1,0,0]
	v_pk_fma_f32 v[56:57], v[58:59], v[94:95], v[56:57] op_sel_hi:[0,1,1] neg_lo:[1,0,0] neg_hi:[1,0,0]
	ds_read_b128 v[28:31], v26 offset:21248
	ds_read_b128 v[32:35], v26 offset:45824
	ds_read_b128 v[36:39], v26 offset:13056
	ds_read_b128 v[72:75], v26 offset:29440
	ds_read_b128 v[76:79], v26 offset:4864
	s_waitcnt lgkmcnt(6)
	v_pk_mul_f32 v[58:59], v[54:55], v[0:1]
	v_pk_mul_f32 v[24:25], v[54:55], v[96:97]
	v_pk_fma_f32 v[58:59], v[56:57], v[2:3], v[58:59]
	v_pk_fma_f32 v[24:25], v[56:57], v[98:99], v[24:25]
	v_add_f32_e32 v58, v58, v59
	v_add_f32_e32 v24, v24, v25
	v_pk_mul_f32 v[4:5], v[4:5], v[22:23] op_sel_hi:[1,0]
	v_add_f32_dpp v58, v58, v58 quad_perm:[1,0,3,2] row_mask:0xf bank_mask:0xf bound_ctrl:1
	v_pk_mul_f32 v[6:7], v[6:7], v[22:23] op_sel_hi:[1,0]
	v_add_f32_dpp v24, v24, v24 quad_perm:[1,0,3,2] row_mask:0xf bank_mask:0xf bound_ctrl:1
	v_add_f32_dpp v58, v58, v58 quad_perm:[2,3,0,1] row_mask:0xf bank_mask:0xf bound_ctrl:1
	v_pk_fma_f32 v[54:55], v[54:55], v[8:9], v[4:5]
	v_pk_fma_f32 v[56:57], v[56:57], v[10:11], v[6:7]
	v_add_f32_dpp v58, v58, v58 row_half_mirror row_mask:0xf bank_mask:0xf bound_ctrl:1
	v_add_f32_dpp v24, v24, v24 quad_perm:[2,3,0,1] row_mask:0xf bank_mask:0xf bound_ctrl:1
	ds_write_b32 v100, v24 offset:4352
	v_add_f32_dpp v58, v58, v58 row_mirror row_mask:0xf bank_mask:0xf bound_ctrl:1
	v_pk_fma_f32 v[54:55], v[58:59], v[12:13], v[54:55] op_sel_hi:[0,1,1] neg_lo:[1,0,0] neg_hi:[1,0,0]
	v_pk_fma_f32 v[56:57], v[58:59], v[14:15], v[56:57] op_sel_hi:[0,1,1] neg_lo:[1,0,0] neg_hi:[1,0,0]
	ds_read_b128 v[80:83], v26 offset:21504
	ds_read_b128 v[84:87], v26 offset:46080
	ds_read2st64_b32 v[20:21], v27 offset0:148 offset1:149
	ds_read_b128 v[88:91], v26 offset:13312
	ds_read_b128 v[92:95], v26 offset:29696
	ds_read_b128 v[96:99], v26 offset:5120
	s_waitcnt lgkmcnt(7)
; __device__ __forceinline__ void rwkv_item(PC p, int wv, int L, int item, LAS unsigned char* lds) {
;     ...
;         for (int s = 0; s < 32; ++s) {
;             const f32x2 r0 = rA, r1 = rB, w0 = wA, w1 = wB, k0 = kA, k1 = kB, b0 = bA, b1 = bB, e0 = eA, e1 = eB; const float vv = vvn;
;             if (s + 1 < 32) RW_LD(s + 1)
;             const f32x2 sa2 = SA * k0 + SB * k1;
;             const float sa = allreduce16(sa2.x + sa2.y);
;             const f32x2 sav = {sa, sa}, vvv = {vv, vv};
;             SA = SA * w0 + (vvv * e0 - sav * b0);
;             SB = SB * w1 + (vvv * e1 - sav * b1);
;             const f32x2 y2 = SA * r0 + SB * r1;
;             float yq = y2.x + y2.y;
;             yq += dppmov<0xB1>(yq); yq += dppmov<0x4E>(yq);
;             Yb[(s * 16 + rowl) * 4 + (kq >> 2)] = yq;
;         }
	v_pk_mul_f32 v[58:59], v[54:55], v[28:29]
	v_pk_mul_f32 v[24:25], v[54:55], v[16:17]
	v_pk_fma_f32 v[58:59], v[56:57], v[30:31], v[58:59]
	v_pk_fma_f32 v[24:25], v[56:57], v[18:19], v[24:25]
	v_add_f32_e32 v58, v58, v59
	v_add_f32_e32 v24, v24, v25
	v_pk_mul_f32 v[32:33], v[32:33], v[22:23] op_sel:[0,1] op_sel_hi:[1,1]
	v_add_f32_dpp v58, v58, v58 quad_perm:[1,0,3,2] row_mask:0xf bank_mask:0xf bound_ctrl:1
	v_pk_mul_f32 v[34:35], v[34:35], v[22:23] op_sel:[0,1] op_sel_hi:[1,1]
	v_add_f32_dpp v24, v24, v24 quad_perm:[1,0,3,2] row_mask:0xf bank_mask:0xf bound_ctrl:1
	v_add_f32_dpp v58, v58, v58 quad_perm:[2,3,0,1] row_mask:0xf bank_mask:0xf bound_ctrl:1
	v_pk_fma_f32 v[54:55], v[54:55], v[36:37], v[32:33]
	v_pk_fma_f32 v[56:57], v[56:57], v[38:39], v[34:35]
	v_add_f32_dpp v58, v58, v58 row_half_mirror row_mask:0xf bank_mask:0xf bound_ctrl:1
	v_add_f32_dpp v24, v24, v24 quad_perm:[2,3,0,1] row_mask:0xf bank_mask:0xf bound_ctrl:1
	ds_write_b32 v100, v24 offset:4608
	v_add_f32_dpp v58, v58, v58 row_mirror row_mask:0xf bank_mask:0xf bound_ctrl:1
	v_pk_fma_f32 v[54:55], v[58:59], v[72:73], v[54:55] op_sel_hi:[0,1,1] neg_lo:[1,0,0] neg_hi:[1,0,0]
	v_pk_fma_f32 v[56:57], v[58:59], v[74:75], v[56:57] op_sel_hi:[0,1,1] neg_lo:[1,0,0] neg_hi:[1,0,0]
	ds_read_b128 v[0:3], v26 offset:21760
	ds_read_b128 v[4:7], v26 offset:46336
	ds_read_b128 v[8:11], v26 offset:13568
	ds_read_b128 v[12:15], v26 offset:29952
	ds_read_b128 v[16:19], v26 offset:5376
	s_waitcnt lgkmcnt(6)
	v_pk_mul_f32 v[58:59], v[54:55], v[80:81]
	v_pk_mul_f32 v[24:25], v[54:55], v[76:77]
	v_pk_fma_f32 v[58:59], v[56:57], v[82:83], v[58:59]
	v_pk_fma_f32 v[24:25], v[56:57], v[78:79], v[24:25]
	v_add_f32_e32 v58, v58, v59
	v_add_f32_e32 v24, v24, v25
	v_pk_mul_f32 v[84:85], v[84:85], v[20:21] op_sel_hi:[1,0]
	v_add_f32_dpp v58, v58, v58 quad_perm:[1,0,3,2] row_mask:0xf bank_mask:0xf bound_ctrl:1
	v_pk_mul_f32 v[86:87], v[86:87], v[20:21] op_sel_hi:[1,0]
	v_add_f32_dpp v24, v24, v24 quad_perm:[1,0,3,2] row_mask:0xf bank_mask:0xf bound_ctrl:1
	v_add_f32_dpp v58, v58, v58 quad_perm:[2,3,0,1] row_mask:0xf bank_mask:0xf bound_ctrl:1
	v_pk_fma_f32 v[54:55], v[54:55], v[88:89], v[84:85]
	v_pk_fma_f32 v[56:57], v[56:57], v[90:91], v[86:87]
	v_add_f32_dpp v58, v58, v58 row_half_mirror row_mask:0xf bank_mask:0xf bound_ctrl:1
	v_add_f32_dpp v24, v24, v24 quad_perm:[2,3,0,1] row_mask:0xf bank_mask:0xf bound_ctrl:1
	ds_write_b32 v100, v24 offset:4864
	v_add_f32_dpp v58, v58, v58 row_mirror row_mask:0xf bank_mask:0xf bound_ctrl:1
	v_pk_fma_f32 v[54:55], v[58:59], v[92:93], v[54:55] op_sel_hi:[0,1,1] neg_lo:[1,0,0] neg_hi:[1,0,0]
	v_pk_fma_f32 v[56:57], v[58:59], v[94:95], v[56:57] op_sel_hi:[0,1,1] neg_lo:[1,0,0] neg_hi:[1,0,0]
	ds_read_b128 v[28:31], v26 offset:22016
	ds_read_b128 v[32:35], v26 offset:46592
	ds_read2st64_b32 v[22:23], v27 offset0:150 offset1:151
	ds_read_b128 v[36:39], v26 offset:13824
	ds_read_b128 v[72:75], v26 offset:30208
	ds_read_b128 v[76:79], v26 offset:5632
	s_waitcnt lgkmcnt(7)
	v_pk_mul_f32 v[58:59], v[54:55], v[0:1]
	v_pk_mul_f32 v[24:25], v[54:55], v[96:97]
	v_pk_fma_f32 v[58:59], v[56:57], v[2:3], v[58:59]
	v_pk_fma_f32 v[24:25], v[56:57], v[98:99], v[24:25]
	v_add_f32_e32 v58, v58, v59
	v_add_f32_e32 v24, v24, v25
	v_pk_mul_f32 v[4:5], v[4:5], v[20:21] op_sel:[0,1] op_sel_hi:[1,1]
	v_add_f32_dpp v58, v58, v58 quad_perm:[1,0,3,2] row_mask:0xf bank_mask:0xf bound_ctrl:1
	v_pk_mul_f32 v[6:7], v[6:7], v[20:21] op_sel:[0,1] op_sel_hi:[1,1]
	v_add_f32_dpp v24, v24, v24 quad_perm:[1,0,3,2] row_mask:0xf bank_mask:0xf bound_ctrl:1
	v_add_f32_dpp v58, v58, v58 quad_perm:[2,3,0,1] row_mask:0xf bank_mask:0xf bound_ctrl:1
	v_pk_fma_f32 v[54:55], v[54:55], v[8:9], v[4:5]
	v_pk_fma_f32 v[56:57], v[56:57], v[10:11], v[6:7]
	v_add_f32_dpp v58, v58, v58 row_half_mirror row_mask:0xf bank_mask:0xf bound_ctrl:1
	v_add_f32_dpp v24, v24, v24 quad_perm:[2,3,0,1] row_mask:0xf bank_mask:0xf bound_ctrl:1
	ds_write_b32 v100, v24 offset:5120
	v_add_f32_dpp v58, v58, v58 row_mirror row_mask:0xf bank_mask:0xf bound_ctrl:1
	v_pk_fma_f32 v[54:55], v[58:59], v[12:13], v[54:55] op_sel_hi:[0,1,1] neg_lo:[1,0,0] neg_hi:[1,0,0]
	v_pk_fma_f32 v[56:57], v[58:59], v[14:15], v[56:57] op_sel_hi:[0,1,1] neg_lo:[1,0,0] neg_hi:[1,0,0]
	ds_read_b128 v[80:83], v26 offset:22272
	ds_read_b128 v[84:87], v26 offset:46848
	ds_read_b128 v[88:91], v26 offset:14080
	ds_read_b128 v[92:95], v26 offset:30464
	ds_read_b128 v[96:99], v26 offset:5888
	s_waitcnt lgkmcnt(6)
	v_pk_mul_f32 v[58:59], v[54:55], v[28:29]
	v_pk_mul_f32 v[24:25], v[54:55], v[16:17]
	v_pk_fma_f32 v[58:59], v[56:57], v[30:31], v[58:59]
	v_pk_fma_f32 v[24:25], v[56:57], v[18:19], v[24:25]
	v_add_f32_e32 v58, v58, v59
	v_add_f32_e32 v24, v24, v25
	v_pk_mul_f32 v[32:33], v[32:33], v[22:23] op_sel_hi:[1,0]
	v_add_f32_dpp v58, v58, v58 quad_perm:[1,0,3,2] row_mask:0xf bank_mask:0xf bound_ctrl:1
	v_pk_mul_f32 v[34:35], v[34:35], v[22:23] op_sel_hi:[1,0]
	v_add_f32_dpp v24, v24, v24 quad_perm:[1,0,3,2] row_mask:0xf bank_mask:0xf bound_ctrl:1
	v_add_f32_dpp v58, v58, v58 quad_perm:[2,3,0,1] row_mask:0xf bank_mask:0xf bound_ctrl:1
	v_pk_fma_f32 v[54:55], v[54:55], v[36:37], v[32:33]
	v_pk_fma_f32 v[56:57], v[56:57], v[38:39], v[34:35]
	v_add_f32_dpp v58, v58, v58 row_half_mirror row_mask:0xf bank_mask:0xf bound_ctrl:1
	v_add_f32_dpp v24, v24, v24 quad_perm:[2,3,0,1] row_mask:0xf bank_mask:0xf bound_ctrl:1
	ds_write_b32 v100, v24 offset:5376
	v_add_f32_dpp v58, v58, v58 row_mirror row_mask:0xf bank_mask:0xf bound_ctrl:1
	v_pk_fma_f32 v[54:55], v[58:59], v[72:73], v[54:55] op_sel_hi:[0,1,1] neg_lo:[1,0,0] neg_hi:[1,0,0]
	v_pk_fma_f32 v[56:57], v[58:59], v[74:75], v[56:57] op_sel_hi:[0,1,1] neg_lo:[1,0,0] neg_hi:[1,0,0]
	ds_read_b128 v[0:3], v26 offset:22528
	ds_read_b128 v[4:7], v26 offset:47104
	ds_read2st64_b32 v[20:21], v27 offset0:152 offset1:153
	ds_read_b128 v[8:11], v26 offset:14336
	ds_read_b128 v[12:15], v26 offset:30720
	ds_read_b128 v[16:19], v26 offset:6144
	s_waitcnt lgkmcnt(7)
; __device__ __forceinline__ void rwkv_item(PC p, int wv, int L, int item, LAS unsigned char* lds) {
;     ...
;         for (int s = 0; s < 32; ++s) {
;             const f32x2 r0 = rA, r1 = rB, w0 = wA, w1 = wB, k0 = kA, k1 = kB, b0 = bA, b1 = bB, e0 = eA, e1 = eB; const float vv = vvn;
;             if (s + 1 < 32) RW_LD(s + 1)
;             const f32x2 sa2 = SA * k0 + SB * k1;
;             const float sa = allreduce16(sa2.x + sa2.y);
;             const f32x2 sav = {sa, sa}, vvv = {vv, vv};
;             SA = SA * w0 + (vvv * e0 - sav * b0);
;             SB = SB * w1 + (vvv * e1 - sav * b1);
;             const f32x2 y2 = SA * r0 + SB * r1;
;             float yq = y2.x + y2.y;
;             yq += dppmov<0xB1>(yq); yq += dppmov<0x4E>(yq);
;             Yb[(s * 16 + rowl) * 4 + (kq >> 2)] = yq;
;         }
	v_pk_mul_f32 v[58:59], v[54:55], v[80:81]
	v_pk_mul_f32 v[24:25], v[54:55], v[76:77]
	v_pk_fma_f32 v[58:59], v[56:57], v[82:83], v[58:59]
	v_pk_fma_f32 v[24:25], v[56:57], v[78:79], v[24:25]
	v_add_f32_e32 v58, v58, v59
	v_add_f32_e32 v24, v24, v25
	v_pk_mul_f32 v[84:85], v[84:85], v[22:23] op_sel:[0,1] op_sel_hi:[1,1]
	v_add_f32_dpp v58, v58, v58 quad_perm:[1,0,3,2] row_mask:0xf bank_mask:0xf bound_ctrl:1
	v_pk_mul_f32 v[86:87], v[86:87], v[22:23] op_sel:[0,1] op_sel_hi:[1,1]
	v_add_f32_dpp v24, v24, v24 quad_perm:[1,0,3,2] row_mask:0xf bank_mask:0xf bound_ctrl:1
	v_add_f32_dpp v58, v58, v58 quad_perm:[2,3,0,1] row_mask:0xf bank_mask:0xf bound_ctrl:1
	v_pk_fma_f32 v[54:55], v[54:55], v[88:89], v[84:85]
	v_pk_fma_f32 v[56:57], v[56:57], v[90:91], v[86:87]
	v_add_f32_dpp v58, v58, v58 row_half_mirror row_mask:0xf bank_mask:0xf bound_ctrl:1
	v_add_f32_dpp v24, v24, v24 quad_perm:[2,3,0,1] row_mask:0xf bank_mask:0xf bound_ctrl:1
	ds_write_b32 v100, v24 offset:5632
	v_add_f32_dpp v58, v58, v58 row_mirror row_mask:0xf bank_mask:0xf bound_ctrl:1
	v_pk_fma_f32 v[54:55], v[58:59], v[92:93], v[54:55] op_sel_hi:[0,1,1] neg_lo:[1,0,0] neg_hi:[1,0,0]
	v_pk_fma_f32 v[56:57], v[58:59], v[94:95], v[56:57] op_sel_hi:[0,1,1] neg_lo:[1,0,0] neg_hi:[1,0,0]
	ds_read_b128 v[28:31], v26 offset:22784
	ds_read_b128 v[32:35], v26 offset:47360
	ds_read_b128 v[36:39], v26 offset:14592
	ds_read_b128 v[72:75], v26 offset:30976
	ds_read_b128 v[76:79], v26 offset:6400
	s_waitcnt lgkmcnt(6)
	v_pk_mul_f32 v[58:59], v[54:55], v[0:1]
	v_pk_mul_f32 v[24:25], v[54:55], v[96:97]
	v_pk_fma_f32 v[58:59], v[56:57], v[2:3], v[58:59]
	v_pk_fma_f32 v[24:25], v[56:57], v[98:99], v[24:25]
	v_add_f32_e32 v58, v58, v59
	v_add_f32_e32 v24, v24, v25
	v_pk_mul_f32 v[4:5], v[4:5], v[20:21] op_sel_hi:[1,0]
	v_add_f32_dpp v58, v58, v58 quad_perm:[1,0,3,2] row_mask:0xf bank_mask:0xf bound_ctrl:1
	v_pk_mul_f32 v[6:7], v[6:7], v[20:21] op_sel_hi:[1,0]
	v_add_f32_dpp v24, v24, v24 quad_perm:[1,0,3,2] row_mask:0xf bank_mask:0xf bound_ctrl:1
	v_add_f32_dpp v58, v58, v58 quad_perm:[2,3,0,1] row_mask:0xf bank_mask:0xf bound_ctrl:1
	v_pk_fma_f32 v[54:55], v[54:55], v[8:9], v[4:5]
	v_pk_fma_f32 v[56:57], v[56:57], v[10:11], v[6:7]
	v_add_f32_dpp v58, v58, v58 row_half_mirror row_mask:0xf bank_mask:0xf bound_ctrl:1
	v_add_f32_dpp v24, v24, v24 quad_perm:[2,3,0,1] row_mask:0xf bank_mask:0xf bound_ctrl:1
	ds_write_b32 v100, v24 offset:5888
	v_add_f32_dpp v58, v58, v58 row_mirror row_mask:0xf bank_mask:0xf bound_ctrl:1
	v_pk_fma_f32 v[54:55], v[58:59], v[12:13], v[54:55] op_sel_hi:[0,1,1] neg_lo:[1,0,0] neg_hi:[1,0,0]
	v_pk_fma_f32 v[56:57], v[58:59], v[14:15], v[56:57] op_sel_hi:[0,1,1] neg_lo:[1,0,0] neg_hi:[1,0,0]
	ds_read_b128 v[80:83], v26 offset:23040
	ds_read_b128 v[84:87], v26 offset:47616
	ds_read2st64_b32 v[22:23], v27 offset0:154 offset1:155
	ds_read_b128 v[88:91], v26 offset:14848
	ds_read_b128 v[92:95], v26 offset:31232
	ds_read_b128 v[96:99], v26 offset:6656
	s_waitcnt lgkmcnt(7)
	v_pk_mul_f32 v[58:59], v[54:55], v[28:29]
	v_pk_mul_f32 v[24:25], v[54:55], v[16:17]
	v_pk_fma_f32 v[58:59], v[56:57], v[30:31], v[58:59]
	v_pk_fma_f32 v[24:25], v[56:57], v[18:19], v[24:25]
	v_add_f32_e32 v58, v58, v59
	v_add_f32_e32 v24, v24, v25
	v_pk_mul_f32 v[32:33], v[32:33], v[20:21] op_sel:[0,1] op_sel_hi:[1,1]
	v_add_f32_dpp v58, v58, v58 quad_perm:[1,0,3,2] row_mask:0xf bank_mask:0xf bound_ctrl:1
	v_pk_mul_f32 v[34:35], v[34:35], v[20:21] op_sel:[0,1] op_sel_hi:[1,1]
	v_add_f32_dpp v24, v24, v24 quad_perm:[1,0,3,2] row_mask:0xf bank_mask:0xf bound_ctrl:1
	v_add_f32_dpp v58, v58, v58 quad_perm:[2,3,0,1] row_mask:0xf bank_mask:0xf bound_ctrl:1
	v_pk_fma_f32 v[54:55], v[54:55], v[36:37], v[32:33]
	v_pk_fma_f32 v[56:57], v[56:57], v[38:39], v[34:35]
	v_add_f32_dpp v58, v58, v58 row_half_mirror row_mask:0xf bank_mask:0xf bound_ctrl:1
	v_add_f32_dpp v24, v24, v24 quad_perm:[2,3,0,1] row_mask:0xf bank_mask:0xf bound_ctrl:1
	ds_write_b32 v100, v24 offset:6144
	v_add_f32_dpp v58, v58, v58 row_mirror row_mask:0xf bank_mask:0xf bound_ctrl:1
	v_pk_fma_f32 v[54:55], v[58:59], v[72:73], v[54:55] op_sel_hi:[0,1,1] neg_lo:[1,0,0] neg_hi:[1,0,0]
	v_pk_fma_f32 v[56:57], v[58:59], v[74:75], v[56:57] op_sel_hi:[0,1,1] neg_lo:[1,0,0] neg_hi:[1,0,0]
	ds_read_b128 v[0:3], v26 offset:23296
	ds_read_b128 v[4:7], v26 offset:47872
	ds_read_b128 v[8:11], v26 offset:15104
	ds_read_b128 v[12:15], v26 offset:31488
	ds_read_b128 v[16:19], v26 offset:6912
	s_waitcnt lgkmcnt(6)
	v_pk_mul_f32 v[58:59], v[54:55], v[80:81]
	v_pk_mul_f32 v[24:25], v[54:55], v[76:77]
	v_pk_fma_f32 v[58:59], v[56:57], v[82:83], v[58:59]
	v_pk_fma_f32 v[24:25], v[56:57], v[78:79], v[24:25]
	v_add_f32_e32 v58, v58, v59
	v_add_f32_e32 v24, v24, v25
	v_pk_mul_f32 v[84:85], v[84:85], v[22:23] op_sel_hi:[1,0]
	v_add_f32_dpp v58, v58, v58 quad_perm:[1,0,3,2] row_mask:0xf bank_mask:0xf bound_ctrl:1
	v_pk_mul_f32 v[86:87], v[86:87], v[22:23] op_sel_hi:[1,0]
	v_add_f32_dpp v24, v24, v24 quad_perm:[1,0,3,2] row_mask:0xf bank_mask:0xf bound_ctrl:1
	v_add_f32_dpp v58, v58, v58 quad_perm:[2,3,0,1] row_mask:0xf bank_mask:0xf bound_ctrl:1
	v_pk_fma_f32 v[54:55], v[54:55], v[88:89], v[84:85]
	v_pk_fma_f32 v[56:57], v[56:57], v[90:91], v[86:87]
	v_add_f32_dpp v58, v58, v58 row_half_mirror row_mask:0xf bank_mask:0xf bound_ctrl:1
	v_add_f32_dpp v24, v24, v24 quad_perm:[2,3,0,1] row_mask:0xf bank_mask:0xf bound_ctrl:1
	ds_write_b32 v100, v24 offset:6400
	v_add_f32_dpp v58, v58, v58 row_mirror row_mask:0xf bank_mask:0xf bound_ctrl:1
	v_pk_fma_f32 v[54:55], v[58:59], v[92:93], v[54:55] op_sel_hi:[0,1,1] neg_lo:[1,0,0] neg_hi:[1,0,0]
	v_pk_fma_f32 v[56:57], v[58:59], v[94:95], v[56:57] op_sel_hi:[0,1,1] neg_lo:[1,0,0] neg_hi:[1,0,0]
	ds_read_b128 v[28:31], v26 offset:23552
	ds_read_b128 v[32:35], v26 offset:48128
	ds_read2st64_b32 v[20:21], v27 offset0:156 offset1:157
	ds_read_b128 v[36:39], v26 offset:15360
	ds_read_b128 v[72:75], v26 offset:31744
	ds_read_b128 v[76:79], v26 offset:7168
	s_waitcnt lgkmcnt(7)
; __device__ __forceinline__ void rwkv_item(PC p, int wv, int L, int item, LAS unsigned char* lds) {
;     ...
;         for (int s = 0; s < 32; ++s) {
;             const f32x2 r0 = rA, r1 = rB, w0 = wA, w1 = wB, k0 = kA, k1 = kB, b0 = bA, b1 = bB, e0 = eA, e1 = eB; const float vv = vvn;
;             if (s + 1 < 32) RW_LD(s + 1)
;             const f32x2 sa2 = SA * k0 + SB * k1;
;             const float sa = allreduce16(sa2.x + sa2.y);
;             const f32x2 sav = {sa, sa}, vvv = {vv, vv};
;             SA = SA * w0 + (vvv * e0 - sav * b0);
;             SB = SB * w1 + (vvv * e1 - sav * b1);
;             const f32x2 y2 = SA * r0 + SB * r1;
;             float yq = y2.x + y2.y;
;             yq += dppmov<0xB1>(yq); yq += dppmov<0x4E>(yq);
;             Yb[(s * 16 + rowl) * 4 + (kq >> 2)] = yq;
;         }
	v_pk_mul_f32 v[58:59], v[54:55], v[0:1]
	v_pk_mul_f32 v[24:25], v[54:55], v[96:97]
	v_pk_fma_f32 v[58:59], v[56:57], v[2:3], v[58:59]
	v_pk_fma_f32 v[24:25], v[56:57], v[98:99], v[24:25]
	v_add_f32_e32 v58, v58, v59
	v_add_f32_e32 v24, v24, v25
	v_pk_mul_f32 v[4:5], v[4:5], v[22:23] op_sel:[0,1] op_sel_hi:[1,1]
	v_add_f32_dpp v58, v58, v58 quad_perm:[1,0,3,2] row_mask:0xf bank_mask:0xf bound_ctrl:1
	v_pk_mul_f32 v[6:7], v[6:7], v[22:23] op_sel:[0,1] op_sel_hi:[1,1]
	v_add_f32_dpp v24, v24, v24 quad_perm:[1,0,3,2] row_mask:0xf bank_mask:0xf bound_ctrl:1
	v_add_f32_dpp v58, v58, v58 quad_perm:[2,3,0,1] row_mask:0xf bank_mask:0xf bound_ctrl:1
	v_pk_fma_f32 v[54:55], v[54:55], v[8:9], v[4:5]
	v_pk_fma_f32 v[56:57], v[56:57], v[10:11], v[6:7]
	v_add_f32_dpp v58, v58, v58 row_half_mirror row_mask:0xf bank_mask:0xf bound_ctrl:1
	v_add_f32_dpp v24, v24, v24 quad_perm:[2,3,0,1] row_mask:0xf bank_mask:0xf bound_ctrl:1
	ds_write_b32 v100, v24 offset:6656
	v_add_f32_dpp v58, v58, v58 row_mirror row_mask:0xf bank_mask:0xf bound_ctrl:1
	v_pk_fma_f32 v[54:55], v[58:59], v[12:13], v[54:55] op_sel_hi:[0,1,1] neg_lo:[1,0,0] neg_hi:[1,0,0]
	v_pk_fma_f32 v[56:57], v[58:59], v[14:15], v[56:57] op_sel_hi:[0,1,1] neg_lo:[1,0,0] neg_hi:[1,0,0]
	ds_read_b128 v[80:83], v26 offset:23808
	ds_read_b128 v[84:87], v26 offset:48384
	ds_read_b128 v[88:91], v26 offset:15616
	ds_read_b128 v[92:95], v26 offset:32000
	ds_read_b128 v[96:99], v26 offset:7424
	s_waitcnt lgkmcnt(6)
	v_pk_mul_f32 v[58:59], v[54:55], v[28:29]
	v_pk_mul_f32 v[24:25], v[54:55], v[16:17]
	v_pk_fma_f32 v[58:59], v[56:57], v[30:31], v[58:59]
	v_pk_fma_f32 v[24:25], v[56:57], v[18:19], v[24:25]
	v_add_f32_e32 v58, v58, v59
	v_add_f32_e32 v24, v24, v25
	v_pk_mul_f32 v[32:33], v[32:33], v[20:21] op_sel_hi:[1,0]
	v_add_f32_dpp v58, v58, v58 quad_perm:[1,0,3,2] row_mask:0xf bank_mask:0xf bound_ctrl:1
	v_pk_mul_f32 v[34:35], v[34:35], v[20:21] op_sel_hi:[1,0]
	v_add_f32_dpp v24, v24, v24 quad_perm:[1,0,3,2] row_mask:0xf bank_mask:0xf bound_ctrl:1
	v_add_f32_dpp v58, v58, v58 quad_perm:[2,3,0,1] row_mask:0xf bank_mask:0xf bound_ctrl:1
	v_pk_fma_f32 v[54:55], v[54:55], v[36:37], v[32:33]
	v_pk_fma_f32 v[56:57], v[56:57], v[38:39], v[34:35]
	v_add_f32_dpp v58, v58, v58 row_half_mirror row_mask:0xf bank_mask:0xf bound_ctrl:1
	v_add_f32_dpp v24, v24, v24 quad_perm:[2,3,0,1] row_mask:0xf bank_mask:0xf bound_ctrl:1
	ds_write_b32 v100, v24 offset:6912
	v_add_f32_dpp v58, v58, v58 row_mirror row_mask:0xf bank_mask:0xf bound_ctrl:1
	v_pk_fma_f32 v[54:55], v[58:59], v[72:73], v[54:55] op_sel_hi:[0,1,1] neg_lo:[1,0,0] neg_hi:[1,0,0]
	v_pk_fma_f32 v[56:57], v[58:59], v[74:75], v[56:57] op_sel_hi:[0,1,1] neg_lo:[1,0,0] neg_hi:[1,0,0]
	ds_read_b128 v[0:3], v26 offset:24064
	ds_read_b128 v[4:7], v26 offset:48640
	ds_read2st64_b32 v[22:23], v27 offset0:158 offset1:159
	ds_read_b128 v[8:11], v26 offset:15872
	ds_read_b128 v[12:15], v26 offset:32256
	ds_read_b128 v[16:19], v26 offset:7680
	s_waitcnt lgkmcnt(7)
	v_pk_mul_f32 v[58:59], v[54:55], v[80:81]
	v_pk_mul_f32 v[24:25], v[54:55], v[76:77]
	v_pk_fma_f32 v[58:59], v[56:57], v[82:83], v[58:59]
	v_pk_fma_f32 v[24:25], v[56:57], v[78:79], v[24:25]
	v_add_f32_e32 v58, v58, v59
	v_add_f32_e32 v24, v24, v25
	v_pk_mul_f32 v[84:85], v[84:85], v[20:21] op_sel:[0,1] op_sel_hi:[1,1]
	v_add_f32_dpp v58, v58, v58 quad_perm:[1,0,3,2] row_mask:0xf bank_mask:0xf bound_ctrl:1
	v_pk_mul_f32 v[86:87], v[86:87], v[20:21] op_sel:[0,1] op_sel_hi:[1,1]
	v_add_f32_dpp v24, v24, v24 quad_perm:[1,0,3,2] row_mask:0xf bank_mask:0xf bound_ctrl:1
	v_add_f32_dpp v58, v58, v58 quad_perm:[2,3,0,1] row_mask:0xf bank_mask:0xf bound_ctrl:1
	v_pk_fma_f32 v[54:55], v[54:55], v[88:89], v[84:85]
	v_pk_fma_f32 v[56:57], v[56:57], v[90:91], v[86:87]
	v_add_f32_dpp v58, v58, v58 row_half_mirror row_mask:0xf bank_mask:0xf bound_ctrl:1
	v_add_f32_dpp v24, v24, v24 quad_perm:[2,3,0,1] row_mask:0xf bank_mask:0xf bound_ctrl:1
	ds_write_b32 v100, v24 offset:7168
	v_add_f32_dpp v58, v58, v58 row_mirror row_mask:0xf bank_mask:0xf bound_ctrl:1
	v_pk_fma_f32 v[54:55], v[58:59], v[92:93], v[54:55] op_sel_hi:[0,1,1] neg_lo:[1,0,0] neg_hi:[1,0,0]
	v_pk_fma_f32 v[56:57], v[58:59], v[94:95], v[56:57] op_sel_hi:[0,1,1] neg_lo:[1,0,0] neg_hi:[1,0,0]
	ds_read_b128 v[28:31], v26 offset:24320
	ds_read_b128 v[32:35], v26 offset:48896
	ds_read_b128 v[36:39], v26 offset:16128
	ds_read_b128 v[72:75], v26 offset:32512
	ds_read_b128 v[76:79], v26 offset:7936
	s_waitcnt lgkmcnt(6)
; __device__ __forceinline__ void rwkv_item(PC p, int wv, int L, int item, LAS unsigned char* lds) {
;     ...
;         for (int s = 0; s < 32; ++s) {
;             const f32x2 r0 = rA, r1 = rB, w0 = wA, w1 = wB, k0 = kA, k1 = kB, b0 = bA, b1 = bB, e0 = eA, e1 = eB; const float vv = vvn;
;             if (s + 1 < 32) RW_LD(s + 1)
;             const f32x2 sa2 = SA * k0 + SB * k1;
;             const float sa = allreduce16(sa2.x + sa2.y);
;             const f32x2 sav = {sa, sa}, vvv = {vv, vv};
;             SA = SA * w0 + (vvv * e0 - sav * b0);
;             SB = SB * w1 + (vvv * e1 - sav * b1);
;             const f32x2 y2 = SA * r0 + SB * r1;
;             float yq = y2.x + y2.y;
;             yq += dppmov<0xB1>(yq); yq += dppmov<0x4E>(yq);
;             Yb[(s * 16 + rowl) * 4 + (kq >> 2)] = yq;
;         }
;     ...
;         if (wv >= 4 && c + 1 < 256) lstore(buf ^ 1);
	v_pk_mul_f32 v[58:59], v[54:55], v[0:1]
	v_pk_mul_f32 v[24:25], v[54:55], v[96:97]
	v_pk_fma_f32 v[58:59], v[56:57], v[2:3], v[58:59]
	v_pk_fma_f32 v[24:25], v[56:57], v[98:99], v[24:25]
	v_add_f32_e32 v58, v58, v59
	v_add_f32_e32 v24, v24, v25
	v_pk_mul_f32 v[4:5], v[4:5], v[22:23] op_sel_hi:[1,0]
	v_add_f32_dpp v58, v58, v58 quad_perm:[1,0,3,2] row_mask:0xf bank_mask:0xf bound_ctrl:1
	v_pk_mul_f32 v[6:7], v[6:7], v[22:23] op_sel_hi:[1,0]
	v_add_f32_dpp v24, v24, v24 quad_perm:[1,0,3,2] row_mask:0xf bank_mask:0xf bound_ctrl:1
	v_add_f32_dpp v58, v58, v58 quad_perm:[2,3,0,1] row_mask:0xf bank_mask:0xf bound_ctrl:1
	v_pk_fma_f32 v[54:55], v[54:55], v[8:9], v[4:5]
	v_pk_fma_f32 v[56:57], v[56:57], v[10:11], v[6:7]
	v_add_f32_dpp v58, v58, v58 row_half_mirror row_mask:0xf bank_mask:0xf bound_ctrl:1
	v_add_f32_dpp v24, v24, v24 quad_perm:[2,3,0,1] row_mask:0xf bank_mask:0xf bound_ctrl:1
	ds_write_b32 v100, v24 offset:7424
	v_add_f32_dpp v58, v58, v58 row_mirror row_mask:0xf bank_mask:0xf bound_ctrl:1
	v_pk_fma_f32 v[54:55], v[58:59], v[12:13], v[54:55] op_sel_hi:[0,1,1] neg_lo:[1,0,0] neg_hi:[1,0,0]
	v_pk_fma_f32 v[56:57], v[58:59], v[14:15], v[56:57] op_sel_hi:[0,1,1] neg_lo:[1,0,0] neg_hi:[1,0,0]
	s_waitcnt lgkmcnt(1)
	v_pk_mul_f32 v[58:59], v[54:55], v[28:29]
	v_pk_mul_f32 v[24:25], v[54:55], v[16:17]
	v_pk_fma_f32 v[58:59], v[56:57], v[30:31], v[58:59]
	v_pk_fma_f32 v[24:25], v[56:57], v[18:19], v[24:25]
	v_add_f32_e32 v58, v58, v59
	v_add_f32_e32 v24, v24, v25
	v_pk_mul_f32 v[32:33], v[32:33], v[22:23] op_sel:[0,1] op_sel_hi:[1,1]
	v_add_f32_dpp v58, v58, v58 quad_perm:[1,0,3,2] row_mask:0xf bank_mask:0xf bound_ctrl:1
	v_pk_mul_f32 v[34:35], v[34:35], v[22:23] op_sel:[0,1] op_sel_hi:[1,1]
	v_add_f32_dpp v24, v24, v24 quad_perm:[1,0,3,2] row_mask:0xf bank_mask:0xf bound_ctrl:1
	v_add_f32_dpp v58, v58, v58 quad_perm:[2,3,0,1] row_mask:0xf bank_mask:0xf bound_ctrl:1
	v_pk_fma_f32 v[54:55], v[54:55], v[36:37], v[32:33]
	v_pk_fma_f32 v[56:57], v[56:57], v[38:39], v[34:35]
	v_add_f32_dpp v58, v58, v58 row_half_mirror row_mask:0xf bank_mask:0xf bound_ctrl:1
	v_add_f32_dpp v24, v24, v24 quad_perm:[2,3,0,1] row_mask:0xf bank_mask:0xf bound_ctrl:1
	ds_write_b32 v100, v24 offset:7680
	v_add_f32_dpp v58, v58, v58 row_mirror row_mask:0xf bank_mask:0xf bound_ctrl:1
	v_pk_fma_f32 v[54:55], v[58:59], v[72:73], v[54:55] op_sel_hi:[0,1,1] neg_lo:[1,0,0] neg_hi:[1,0,0]
	v_pk_fma_f32 v[56:57], v[58:59], v[74:75], v[56:57] op_sel_hi:[0,1,1] neg_lo:[1,0,0] neg_hi:[1,0,0]
	v_pk_mul_f32 v[24:25], v[54:55], v[76:77]
	s_nop 0
	v_pk_fma_f32 v[24:25], v[56:57], v[78:79], v[24:25]
	s_nop 0
	v_add_f32_e32 v24, v24, v25
	s_nop 1
	v_add_f32_dpp v24, v24, v24 quad_perm:[1,0,3,2] row_mask:0xf bank_mask:0xf bound_ctrl:1
	s_nop 1
	v_add_f32_dpp v24, v24, v24 quad_perm:[2,3,0,1] row_mask:0xf bank_mask:0xf bound_ctrl:1
	ds_write_b32 v100, v24 offset:7936
.LBB0_408:
	s_xor_b64 s[12:13], s[12:13], -1
	s_andn2_b64 vcc, exec, s[12:13]
	s_cbranch_vccnz .LBB0_410
	s_xor_b32 s12, s15, 1
	s_mul_i32 s12, s12, 0xc000
	v_add_u32_e32 v53, s12, v60
	s_and_b64 vcc, exec, s[8:9]
	s_cbranch_vccz .Lrw_w67_L0
	s_cmpk_eq_i32 s18, 0
	s_cbranch_scc1 .Lrw_w67_L0
	s_cmpk_eq_i32 s18, 0xfe
	s_cbranch_scc1 .Lrw_w45_last_L0
	s_waitcnt vmcnt(7)
	s_branch .Lrw_cvt_go_L0
.Lrw_w45_last_L0:
	s_waitcnt vmcnt(1)
	s_branch .Lrw_cvt_go_L0
.Lrw_w67_L0:
	s_cmpk_eq_i32 s18, 0xfe
	s_cbranch_scc1 .Lrw_cvt_last_L0
	s_waitcnt vmcnt(6)
	s_branch .Lrw_cvt_go_L0
